# pool-GEMM phase: the 4x32 sample units spread over blocks 0..127 (one each) instead of four sequential units on blocks 0..31
# baseline (speedup 1.0000x reference)
; template <bool RS, class Epi, class RowF>
; DI void gemm_sample(const bfr* __restrict__ A, int lda, const bfr* __restrict__ Bt, int ldb, int K, int N, char* smem, Epi epi, RowF rowf) {
;   const int tid = threadIdx.x, lane = tid & 63, wid = tid >> 6, r = lane & 31, hl = lane >> 5;
;   float* red = (float*)smem;
;   const int nun = 4 * (N >> 5);
;   for (int u = blockIdx.x; u < nun; u += gridDim.x) {
;     const int mu = u & 3, nu = u >> 2;
;     const int kq = K >> 2, k0 = wid * kq;
;     const bfr* ap = A + (size_t)(NPR + mu * 32 + r) * lda + k0 + hl * 8;
;     const bfr* bp = Bt + ((size_t)(k0 >> 5) * ldb + nu * 32 + r) * 32 + hl * 8;
; DI void phase_gemm_pool(const Params& p, char* smem) {
;     ...
;   for (int g = 0; g < 4; ++g) {
;     const float* bp = p.b_pool + g * 256;
;     const float* sc = p.pool_scale + g * 256;
;     gemm_sample<false>(p.MIX + g * 256, 1024, p.WtPool + (size_t)g * 65536, 256, 256, 256, smem,
.LBB0_1368:
	s_or_b64 exec, exec, s[0:1]
	v_cmp_gt_i32_e32 vcc, 15, v0
	v_cmp_lt_i32_e64 s[0:1], 13, v1
	s_and_b64 s[0:1], vcc, s[0:1]
	s_and_saveexec_b64 s[2:3], s[0:1]
	s_cbranch_execz .LBB0_1395
	v_lshrrev_b32_e32 v0, 6, v196
	v_and_b32_e32 v1, 63, v196
	v_bfe_u32 v5, v196, 6, 2
	v_lshrrev_b32_e32 v6, 5, v196
	v_lshlrev_b32_e32 v2, 2, v1
	v_and_or_b32 v31, v6, 24, v5
	v_add_u32_e32 v6, 4, v0
	v_lshl_or_b32 v32, v6, 8, v2
	v_lshlrev_b32_e32 v6, 1, v6
	s_load_dwordx4 s[8:11], s[92:93], 0x150
	s_waitcnt lgkmcnt(0)
	s_load_dwordx4 s[12:15], s[92:93], 0xc0
	s_load_dwordx2 s[16:17], s[92:93], 0x168
	s_load_dwordx2 s[18:19], s[92:93], 0x1a0
	v_and_b32_e32 v1, 0x3c0, v196
	v_lshlrev_b32_e32 v4, 12, v0
	v_and_or_b32 v33, v6, 56, v5
	v_add_u32_e32 v6, 8, v0
	v_add_u32_e32 v0, 12, v0
	v_and_b32_e32 v28, 31, v196
	s_cmp_ge_u32 s34, 0x80
	s_cselect_b32 s100, 0x80, 32
	s_cselect_b32 s98, 1, 0
	s_and_b32 s99, s46, 31
	s_cmp_eq_u32 s98, 1
	s_cselect_b32 s99, s99, s46
	s_lshr_b32 s101, s46, 5
	s_cmp_eq_u32 s98, 1
	s_cselect_b32 s101, s101, -1
	s_cmp_lt_i32 s46, s100
	v_bfe_u32 v3, v196, 5, 1
	v_mov_b32_e32 v19, 0
	v_lshl_or_b32 v36, v0, 8, v2
	v_lshlrev_b32_e32 v0, 1, v0
	v_lshlrev_b32_e32 v18, 1, v1
	s_cselect_b64 s[0:1], -1, 0
	v_lshl_or_b32 v16, v1, 3, v28
	v_lshl_or_b32 v30, v1, 2, v2
	v_and_or_b32 v37, v0, 56, v5
	v_lshl_add_u64 v[0:1], s[10:11], 0, v[18:19]
	v_lshlrev_b32_e32 v18, 4, v3
	v_lshl_or_b32 v34, v6, 8, v2
	v_lshlrev_b32_e32 v6, 1, v6
	v_lshl_add_u64 v[20:21], v[0:1], 0, v[18:19]
	v_cndmask_b32_e64 v0, 0, 1, s[0:1]
	v_mov_b32_e32 v17, v19
	v_lshlrev_b32_e32 v29, 2, v3
	v_and_or_b32 v35, v6, 56, v5
	s_waitcnt lgkmcnt(0)
	v_lshl_add_u64 v[22:23], s[18:19], 0, v[18:19]
	s_lshl_b32 s24, s99, 3
	s_lshl_b32 s25, s99, 5
	s_mov_b32 s5, 0
	v_cmp_ne_u32_e64 s[0:1], 1, v0
	s_movk_i32 s26, 0x4000
	v_add_u32_e32 v38, v2, v4
	s_mov_b32 s27, 0
	s_branch .LBB0_1371

; template <bool RS, class Epi, class RowF>
; DI void gemm_sample(const bfr* __restrict__ A, int lda, const bfr* __restrict__ Bt, int ldb, int K, int N, char* smem, Epi epi, RowF rowf) {
;     ...
;   for (int u = blockIdx.x; u < nun; u += gridDim.x) {
;     const int mu = u & 3, nu = u >> 2;
;     const int kq = K >> 2, k0 = wid * kq;
;     const bfr* ap = A + (size_t)(NPR + mu * 32 + r) * lda + k0 + hl * 8;
;     const bfr* bp = Bt + ((size_t)(k0 >> 5) * ldb + nu * 32 + r) * 32 + hl * 8;
; DI void phase_gemm_pool(const Params& p, char* smem) {
;     ...
;   for (int g = 0; g < 4; ++g) {
;     const float* bp = p.b_pool + g * 256;
;     const float* sc = p.pool_scale + g * 256;
;     gemm_sample<false>(p.MIX + g * 256, 1024, p.WtPool + (size_t)g * 65536, 256, 256, 256, smem,
.LBB0_1371:
	s_and_b64 vcc, exec, s[0:1]
	s_cbranch_vccnz .LBB0_1370
	s_cmp_eq_u32 s101, -1
	s_cbranch_scc1 .Lp14_gok
	s_cmp_eq_u32 s27, s101
	s_cbranch_scc0 .LBB0_1370
.Lp14_gok:
	s_lshl_b32 s4, s27, 8
	v_readlane_b32 s22, v254, 0
	s_lshl_b64 s[10:11], s[4:5], 2
	v_readlane_b32 s23, v254, 1
	s_add_u32 s6, s12, s10
	s_load_dword s22, s[22:23], 0x10
	s_addc_u32 s7, s13, s11
	s_add_u32 s10, s14, s10
	s_addc_u32 s11, s15, s11
	s_lshl_b32 s4, s27, 9
	s_lshl_b32 s20, s27, 17
	s_mov_b32 s21, s5
	v_lshl_add_u64 v[26:27], v[22:23], 0, s[20:21]
	s_add_u32 s20, s16, s4
	s_addc_u32 s21, s17, 0
	s_waitcnt lgkmcnt(0)
	s_lshr_b32 s22, s22, 16
	s_cmp_lg_u32 s22, 0
	s_cselect_b64 s[22:23], -1, 0
	s_cmp_lg_u64 s[22:23], 0
	s_addc_u32 s28, s34, 0
	s_add_u32 s22, s8, s4
	v_lshl_add_u64 v[24:25], v[20:21], 0, s[4:5]
	s_addc_u32 s23, s9, 0
	s_lshl_b32 s4, s28, 3
	s_lshl_b32 s29, s28, 5
	s_mov_b32 s30, s25
	s_mov_b32 s31, s24
	s_mov_b32 s33, s99
